# compact hand-written in-proj epilogue also for the gelu panels
# baseline (speedup 1.0000x reference)
.LBB0_272:
	s_lshl_b32 s100, 1, s49
	s_and_b32 s101, s100, 0x1fa0
	s_cbranch_scc1 .Lepi_raw
	s_and_b32 s101, s100, 0x604c
	s_cbranch_scc1 .Lepi_silu
	s_and_b32 s101, s100, 0x3
	s_cbranch_scc1 .Lepi_gelu
	s_branch .Lepi_std

.Lepi_gelu:
	v_mov_b64_e32 v[128:129], s[50:51]
	v_mad_u64_u32 v[128:129], s[100:101], v174, s70, v[128:129]
	s_lshl_b32 s100, s49, 9
	s_nop 0
	v_lshl_add_u32 v190, v144, 1, s100
	v_lshl_add_u64 v[128:129], v[128:129], 0, v[190:191]
	s_mov_b64 s[100:101], 0x1e000
	v_mul_f32_e32 v60, v60, v172
	v_mul_f32_e32 v61, v61, v172
	v_mul_f32_e32 v62, v62, v172
	v_mul_f32_e32 v63, v63, v172
	v_mul_f32_e32 v56, v56, v172
	v_mul_f32_e32 v57, v57, v172
	v_mul_f32_e32 v58, v58, v172
	v_mul_f32_e32 v59, v59, v172
	v_mul_f32_e32 v202, 0x3d372713, v60
	v_mul_f32_e32 v203, 0x3d372713, v61
	v_mul_f32_e32 v204, 0x3d372713, v62
	v_mul_f32_e32 v205, 0x3d372713, v63
	v_mul_f32_e32 v206, 0x3d372713, v56
	v_mul_f32_e32 v207, 0x3d372713, v57
	v_mul_f32_e32 v208, 0x3d372713, v58
	v_mul_f32_e32 v209, 0x3d372713, v59
	v_mul_f32_e32 v202, v60, v202
	v_mul_f32_e32 v203, v61, v203
	v_mul_f32_e32 v204, v62, v204
	v_mul_f32_e32 v205, v63, v205
	v_mul_f32_e32 v206, v56, v206
	v_mul_f32_e32 v207, v57, v207
	v_mul_f32_e32 v208, v58, v208
	v_mul_f32_e32 v209, v59, v209
	v_fma_f32 v202, v60, v202, v60
	v_fma_f32 v203, v61, v203, v61
	v_fma_f32 v204, v62, v204, v62
	v_fma_f32 v205, v63, v205, v63
	v_fma_f32 v206, v56, v206, v56
	v_fma_f32 v207, v57, v207, v57
	v_fma_f32 v208, v58, v208, v58
	v_fma_f32 v209, v59, v209, v59
	v_mul_f32_e32 v202, 0x3f4c422a, v202
	v_mul_f32_e32 v203, 0x3f4c422a, v203
	v_mul_f32_e32 v204, 0x3f4c422a, v204
	v_mul_f32_e32 v205, 0x3f4c422a, v205
	v_mul_f32_e32 v206, 0x3f4c422a, v206
	v_mul_f32_e32 v207, 0x3f4c422a, v207
	v_mul_f32_e32 v208, 0x3f4c422a, v208
	v_mul_f32_e32 v209, 0x3f4c422a, v209
	v_mul_f32_e32 v202, 0xc038aa3b, v202
	v_mul_f32_e32 v203, 0xc038aa3b, v203
	v_mul_f32_e32 v204, 0xc038aa3b, v204
	v_mul_f32_e32 v205, 0xc038aa3b, v205
	v_mul_f32_e32 v206, 0xc038aa3b, v206
	v_mul_f32_e32 v207, 0xc038aa3b, v207
	v_mul_f32_e32 v208, 0xc038aa3b, v208
	v_mul_f32_e32 v209, 0xc038aa3b, v209
	v_exp_f32_e32 v202, v202
	v_exp_f32_e32 v203, v203
	v_exp_f32_e32 v204, v204
	v_exp_f32_e32 v205, v205
	v_exp_f32_e32 v206, v206
	v_exp_f32_e32 v207, v207
	v_exp_f32_e32 v208, v208
	v_exp_f32_e32 v209, v209
	v_add_f32_e32 v202, 1.0, v202
	v_add_f32_e32 v203, 1.0, v203
	v_add_f32_e32 v204, 1.0, v204
	v_add_f32_e32 v205, 1.0, v205
	v_add_f32_e32 v206, 1.0, v206
	v_add_f32_e32 v207, 1.0, v207
	v_add_f32_e32 v208, 1.0, v208
	v_add_f32_e32 v209, 1.0, v209
	v_rcp_f32_e32 v202, v202
	v_rcp_f32_e32 v203, v203
	v_rcp_f32_e32 v204, v204
	v_rcp_f32_e32 v205, v205
	v_rcp_f32_e32 v206, v206
	v_rcp_f32_e32 v207, v207
	v_rcp_f32_e32 v208, v208
	v_rcp_f32_e32 v209, v209
	v_mul_f32_e32 v60, v60, v202
	v_mul_f32_e32 v61, v61, v203
	v_mul_f32_e32 v62, v62, v204
	v_mul_f32_e32 v63, v63, v205
	v_mul_f32_e32 v56, v56, v206
	v_mul_f32_e32 v57, v57, v207
	v_mul_f32_e32 v58, v58, v208
	v_mul_f32_e32 v59, v59, v209
	v_cvt_pk_bf16_f32 v60, v60, v61
	v_cvt_pk_bf16_f32 v61, v62, v63
	v_cvt_pk_bf16_f32 v62, v56, v57
	v_cvt_pk_bf16_f32 v63, v58, v59
	global_store_dwordx4 v[128:129], v[60:63], off
	v_mul_f32_e32 v124, v124, v172
	v_mul_f32_e32 v125, v125, v172
	v_mul_f32_e32 v126, v126, v172
	v_mul_f32_e32 v127, v127, v172
	v_mul_f32_e32 v120, v120, v172
	v_mul_f32_e32 v121, v121, v172
	v_mul_f32_e32 v122, v122, v172
	v_mul_f32_e32 v123, v123, v172
	v_mul_f32_e32 v202, 0x3d372713, v124
	v_mul_f32_e32 v203, 0x3d372713, v125
	v_mul_f32_e32 v204, 0x3d372713, v126
	v_mul_f32_e32 v205, 0x3d372713, v127
	v_mul_f32_e32 v206, 0x3d372713, v120
	v_mul_f32_e32 v207, 0x3d372713, v121
	v_mul_f32_e32 v208, 0x3d372713, v122
	v_mul_f32_e32 v209, 0x3d372713, v123
	v_mul_f32_e32 v202, v124, v202
	v_mul_f32_e32 v203, v125, v203
	v_mul_f32_e32 v204, v126, v204
	v_mul_f32_e32 v205, v127, v205
	v_mul_f32_e32 v206, v120, v206
	v_mul_f32_e32 v207, v121, v207
	v_mul_f32_e32 v208, v122, v208
	v_mul_f32_e32 v209, v123, v209
	v_fma_f32 v202, v124, v202, v124
	v_fma_f32 v203, v125, v203, v125
	v_fma_f32 v204, v126, v204, v126
	v_fma_f32 v205, v127, v205, v127
	v_fma_f32 v206, v120, v206, v120
	v_fma_f32 v207, v121, v207, v121
	v_fma_f32 v208, v122, v208, v122
	v_fma_f32 v209, v123, v209, v123
	v_mul_f32_e32 v202, 0x3f4c422a, v202
	v_mul_f32_e32 v203, 0x3f4c422a, v203
	v_mul_f32_e32 v204, 0x3f4c422a, v204
	v_mul_f32_e32 v205, 0x3f4c422a, v205
	v_mul_f32_e32 v206, 0x3f4c422a, v206
	v_mul_f32_e32 v207, 0x3f4c422a, v207
	v_mul_f32_e32 v208, 0x3f4c422a, v208
	v_mul_f32_e32 v209, 0x3f4c422a, v209
	v_mul_f32_e32 v202, 0xc038aa3b, v202
	v_mul_f32_e32 v203, 0xc038aa3b, v203
	v_mul_f32_e32 v204, 0xc038aa3b, v204
	v_mul_f32_e32 v205, 0xc038aa3b, v205
	v_mul_f32_e32 v206, 0xc038aa3b, v206
	v_mul_f32_e32 v207, 0xc038aa3b, v207
	v_mul_f32_e32 v208, 0xc038aa3b, v208
	v_mul_f32_e32 v209, 0xc038aa3b, v209
	v_exp_f32_e32 v202, v202
	v_exp_f32_e32 v203, v203
	v_exp_f32_e32 v204, v204
	v_exp_f32_e32 v205, v205
	v_exp_f32_e32 v206, v206
	v_exp_f32_e32 v207, v207
	v_exp_f32_e32 v208, v208
	v_exp_f32_e32 v209, v209
	v_add_f32_e32 v202, 1.0, v202
	v_add_f32_e32 v203, 1.0, v203
	v_add_f32_e32 v204, 1.0, v204
	v_add_f32_e32 v205, 1.0, v205
	v_add_f32_e32 v206, 1.0, v206
	v_add_f32_e32 v207, 1.0, v207
	v_add_f32_e32 v208, 1.0, v208
	v_add_f32_e32 v209, 1.0, v209
	v_rcp_f32_e32 v202, v202
	v_rcp_f32_e32 v203, v203
	v_rcp_f32_e32 v204, v204
	v_rcp_f32_e32 v205, v205
	v_rcp_f32_e32 v206, v206
	v_rcp_f32_e32 v207, v207
	v_rcp_f32_e32 v208, v208
	v_rcp_f32_e32 v209, v209
	v_mul_f32_e32 v124, v124, v202
	v_mul_f32_e32 v125, v125, v203
	v_mul_f32_e32 v126, v126, v204
	v_mul_f32_e32 v127, v127, v205
	v_mul_f32_e32 v120, v120, v206
	v_mul_f32_e32 v121, v121, v207
	v_mul_f32_e32 v122, v122, v208
	v_mul_f32_e32 v123, v123, v209
	v_cvt_pk_bf16_f32 v124, v124, v125
	v_cvt_pk_bf16_f32 v125, v126, v127
	v_cvt_pk_bf16_f32 v126, v120, v121
	v_cvt_pk_bf16_f32 v127, v122, v123
	global_store_dwordx4 v[128:129], v[124:127], off offset:256
	v_lshl_add_u64 v[128:129], v[128:129], 0, s[100:101]
	v_mul_f32_e32 v52, v52, v170
	v_mul_f32_e32 v53, v53, v170
	v_mul_f32_e32 v54, v54, v170
	v_mul_f32_e32 v55, v55, v170
	v_mul_f32_e32 v48, v48, v170
	v_mul_f32_e32 v49, v49, v170
	v_mul_f32_e32 v50, v50, v170
	v_mul_f32_e32 v51, v51, v170
	v_mul_f32_e32 v202, 0x3d372713, v52
	v_mul_f32_e32 v203, 0x3d372713, v53
	v_mul_f32_e32 v204, 0x3d372713, v54
	v_mul_f32_e32 v205, 0x3d372713, v55
	v_mul_f32_e32 v206, 0x3d372713, v48
	v_mul_f32_e32 v207, 0x3d372713, v49
	v_mul_f32_e32 v208, 0x3d372713, v50
	v_mul_f32_e32 v209, 0x3d372713, v51
	v_mul_f32_e32 v202, v52, v202
	v_mul_f32_e32 v203, v53, v203
	v_mul_f32_e32 v204, v54, v204
	v_mul_f32_e32 v205, v55, v205
	v_mul_f32_e32 v206, v48, v206
	v_mul_f32_e32 v207, v49, v207
	v_mul_f32_e32 v208, v50, v208
	v_mul_f32_e32 v209, v51, v209
	v_fma_f32 v202, v52, v202, v52
	v_fma_f32 v203, v53, v203, v53
	v_fma_f32 v204, v54, v204, v54
	v_fma_f32 v205, v55, v205, v55
	v_fma_f32 v206, v48, v206, v48
	v_fma_f32 v207, v49, v207, v49
	v_fma_f32 v208, v50, v208, v50
	v_fma_f32 v209, v51, v209, v51
	v_mul_f32_e32 v202, 0x3f4c422a, v202
	v_mul_f32_e32 v203, 0x3f4c422a, v203
	v_mul_f32_e32 v204, 0x3f4c422a, v204
	v_mul_f32_e32 v205, 0x3f4c422a, v205
	v_mul_f32_e32 v206, 0x3f4c422a, v206
	v_mul_f32_e32 v207, 0x3f4c422a, v207
	v_mul_f32_e32 v208, 0x3f4c422a, v208
	v_mul_f32_e32 v209, 0x3f4c422a, v209
	v_mul_f32_e32 v202, 0xc038aa3b, v202
	v_mul_f32_e32 v203, 0xc038aa3b, v203
	v_mul_f32_e32 v204, 0xc038aa3b, v204
	v_mul_f32_e32 v205, 0xc038aa3b, v205
	v_mul_f32_e32 v206, 0xc038aa3b, v206
	v_mul_f32_e32 v207, 0xc038aa3b, v207
	v_mul_f32_e32 v208, 0xc038aa3b, v208
	v_mul_f32_e32 v209, 0xc038aa3b, v209
	v_exp_f32_e32 v202, v202
	v_exp_f32_e32 v203, v203
	v_exp_f32_e32 v204, v204
	v_exp_f32_e32 v205, v205
	v_exp_f32_e32 v206, v206
	v_exp_f32_e32 v207, v207
	v_exp_f32_e32 v208, v208
	v_exp_f32_e32 v209, v209
	v_add_f32_e32 v202, 1.0, v202
	v_add_f32_e32 v203, 1.0, v203
	v_add_f32_e32 v204, 1.0, v204
	v_add_f32_e32 v205, 1.0, v205
	v_add_f32_e32 v206, 1.0, v206
	v_add_f32_e32 v207, 1.0, v207
	v_add_f32_e32 v208, 1.0, v208
	v_add_f32_e32 v209, 1.0, v209
	v_rcp_f32_e32 v202, v202
	v_rcp_f32_e32 v203, v203
	v_rcp_f32_e32 v204, v204
	v_rcp_f32_e32 v205, v205
	v_rcp_f32_e32 v206, v206
	v_rcp_f32_e32 v207, v207
	v_rcp_f32_e32 v208, v208
	v_rcp_f32_e32 v209, v209
	v_mul_f32_e32 v52, v52, v202
	v_mul_f32_e32 v53, v53, v203
	v_mul_f32_e32 v54, v54, v204
	v_mul_f32_e32 v55, v55, v205
	v_mul_f32_e32 v48, v48, v206
	v_mul_f32_e32 v49, v49, v207
	v_mul_f32_e32 v50, v50, v208
	v_mul_f32_e32 v51, v51, v209
	v_cvt_pk_bf16_f32 v52, v52, v53
	v_cvt_pk_bf16_f32 v53, v54, v55
	v_cvt_pk_bf16_f32 v54, v48, v49
	v_cvt_pk_bf16_f32 v55, v50, v51
	global_store_dwordx4 v[128:129], v[52:55], off
	v_mul_f32_e32 v116, v116, v170
	v_mul_f32_e32 v117, v117, v170
	v_mul_f32_e32 v118, v118, v170
	v_mul_f32_e32 v119, v119, v170
	v_mul_f32_e32 v112, v112, v170
	v_mul_f32_e32 v113, v113, v170
	v_mul_f32_e32 v114, v114, v170
	v_mul_f32_e32 v115, v115, v170
	v_mul_f32_e32 v202, 0x3d372713, v116
	v_mul_f32_e32 v203, 0x3d372713, v117
	v_mul_f32_e32 v204, 0x3d372713, v118
	v_mul_f32_e32 v205, 0x3d372713, v119
	v_mul_f32_e32 v206, 0x3d372713, v112
	v_mul_f32_e32 v207, 0x3d372713, v113
	v_mul_f32_e32 v208, 0x3d372713, v114
	v_mul_f32_e32 v209, 0x3d372713, v115
	v_mul_f32_e32 v202, v116, v202
	v_mul_f32_e32 v203, v117, v203
	v_mul_f32_e32 v204, v118, v204
	v_mul_f32_e32 v205, v119, v205
	v_mul_f32_e32 v206, v112, v206
	v_mul_f32_e32 v207, v113, v207
	v_mul_f32_e32 v208, v114, v208
	v_mul_f32_e32 v209, v115, v209
	v_fma_f32 v202, v116, v202, v116
	v_fma_f32 v203, v117, v203, v117
	v_fma_f32 v204, v118, v204, v118
	v_fma_f32 v205, v119, v205, v119
	v_fma_f32 v206, v112, v206, v112
	v_fma_f32 v207, v113, v207, v113
	v_fma_f32 v208, v114, v208, v114
	v_fma_f32 v209, v115, v209, v115
	v_mul_f32_e32 v202, 0x3f4c422a, v202
	v_mul_f32_e32 v203, 0x3f4c422a, v203
	v_mul_f32_e32 v204, 0x3f4c422a, v204
	v_mul_f32_e32 v205, 0x3f4c422a, v205
	v_mul_f32_e32 v206, 0x3f4c422a, v206
	v_mul_f32_e32 v207, 0x3f4c422a, v207
	v_mul_f32_e32 v208, 0x3f4c422a, v208
	v_mul_f32_e32 v209, 0x3f4c422a, v209
	v_mul_f32_e32 v202, 0xc038aa3b, v202
	v_mul_f32_e32 v203, 0xc038aa3b, v203
	v_mul_f32_e32 v204, 0xc038aa3b, v204
	v_mul_f32_e32 v205, 0xc038aa3b, v205
	v_mul_f32_e32 v206, 0xc038aa3b, v206
	v_mul_f32_e32 v207, 0xc038aa3b, v207
	v_mul_f32_e32 v208, 0xc038aa3b, v208
	v_mul_f32_e32 v209, 0xc038aa3b, v209
	v_exp_f32_e32 v202, v202
	v_exp_f32_e32 v203, v203
	v_exp_f32_e32 v204, v204
	v_exp_f32_e32 v205, v205
	v_exp_f32_e32 v206, v206
	v_exp_f32_e32 v207, v207
	v_exp_f32_e32 v208, v208
	v_exp_f32_e32 v209, v209
	v_add_f32_e32 v202, 1.0, v202
	v_add_f32_e32 v203, 1.0, v203
	v_add_f32_e32 v204, 1.0, v204
	v_add_f32_e32 v205, 1.0, v205
	v_add_f32_e32 v206, 1.0, v206
	v_add_f32_e32 v207, 1.0, v207
	v_add_f32_e32 v208, 1.0, v208
	v_add_f32_e32 v209, 1.0, v209
	v_rcp_f32_e32 v202, v202
	v_rcp_f32_e32 v203, v203
	v_rcp_f32_e32 v204, v204
	v_rcp_f32_e32 v205, v205
	v_rcp_f32_e32 v206, v206
	v_rcp_f32_e32 v207, v207
	v_rcp_f32_e32 v208, v208
	v_rcp_f32_e32 v209, v209
	v_mul_f32_e32 v116, v116, v202
	v_mul_f32_e32 v117, v117, v203
	v_mul_f32_e32 v118, v118, v204
	v_mul_f32_e32 v119, v119, v205
	v_mul_f32_e32 v112, v112, v206
	v_mul_f32_e32 v113, v113, v207
	v_mul_f32_e32 v114, v114, v208
	v_mul_f32_e32 v115, v115, v209
	v_cvt_pk_bf16_f32 v116, v116, v117
	v_cvt_pk_bf16_f32 v117, v118, v119
	v_cvt_pk_bf16_f32 v118, v112, v113
	v_cvt_pk_bf16_f32 v119, v114, v115
	global_store_dwordx4 v[128:129], v[116:119], off offset:256
	v_lshl_add_u64 v[128:129], v[128:129], 0, s[100:101]
	v_mul_f32_e32 v44, v44, v168
	v_mul_f32_e32 v45, v45, v168
	v_mul_f32_e32 v46, v46, v168
	v_mul_f32_e32 v47, v47, v168
	v_mul_f32_e32 v40, v40, v168
	v_mul_f32_e32 v41, v41, v168
	v_mul_f32_e32 v42, v42, v168
	v_mul_f32_e32 v43, v43, v168
	v_mul_f32_e32 v202, 0x3d372713, v44
	v_mul_f32_e32 v203, 0x3d372713, v45
	v_mul_f32_e32 v204, 0x3d372713, v46
	v_mul_f32_e32 v205, 0x3d372713, v47
	v_mul_f32_e32 v206, 0x3d372713, v40
	v_mul_f32_e32 v207, 0x3d372713, v41
	v_mul_f32_e32 v208, 0x3d372713, v42
	v_mul_f32_e32 v209, 0x3d372713, v43
	v_mul_f32_e32 v202, v44, v202
	v_mul_f32_e32 v203, v45, v203
	v_mul_f32_e32 v204, v46, v204
	v_mul_f32_e32 v205, v47, v205
	v_mul_f32_e32 v206, v40, v206
	v_mul_f32_e32 v207, v41, v207
	v_mul_f32_e32 v208, v42, v208
	v_mul_f32_e32 v209, v43, v209
	v_fma_f32 v202, v44, v202, v44
	v_fma_f32 v203, v45, v203, v45
	v_fma_f32 v204, v46, v204, v46
	v_fma_f32 v205, v47, v205, v47
	v_fma_f32 v206, v40, v206, v40
	v_fma_f32 v207, v41, v207, v41
	v_fma_f32 v208, v42, v208, v42
	v_fma_f32 v209, v43, v209, v43
	v_mul_f32_e32 v202, 0x3f4c422a, v202
	v_mul_f32_e32 v203, 0x3f4c422a, v203
	v_mul_f32_e32 v204, 0x3f4c422a, v204
	v_mul_f32_e32 v205, 0x3f4c422a, v205
	v_mul_f32_e32 v206, 0x3f4c422a, v206
	v_mul_f32_e32 v207, 0x3f4c422a, v207
	v_mul_f32_e32 v208, 0x3f4c422a, v208
	v_mul_f32_e32 v209, 0x3f4c422a, v209
	v_mul_f32_e32 v202, 0xc038aa3b, v202
	v_mul_f32_e32 v203, 0xc038aa3b, v203
	v_mul_f32_e32 v204, 0xc038aa3b, v204
	v_mul_f32_e32 v205, 0xc038aa3b, v205
	v_mul_f32_e32 v206, 0xc038aa3b, v206
	v_mul_f32_e32 v207, 0xc038aa3b, v207
	v_mul_f32_e32 v208, 0xc038aa3b, v208
	v_mul_f32_e32 v209, 0xc038aa3b, v209
	v_exp_f32_e32 v202, v202
	v_exp_f32_e32 v203, v203
	v_exp_f32_e32 v204, v204
	v_exp_f32_e32 v205, v205
	v_exp_f32_e32 v206, v206
	v_exp_f32_e32 v207, v207
	v_exp_f32_e32 v208, v208
	v_exp_f32_e32 v209, v209
	v_add_f32_e32 v202, 1.0, v202
	v_add_f32_e32 v203, 1.0, v203
	v_add_f32_e32 v204, 1.0, v204
	v_add_f32_e32 v205, 1.0, v205
	v_add_f32_e32 v206, 1.0, v206
	v_add_f32_e32 v207, 1.0, v207
	v_add_f32_e32 v208, 1.0, v208
	v_add_f32_e32 v209, 1.0, v209
	v_rcp_f32_e32 v202, v202
	v_rcp_f32_e32 v203, v203
	v_rcp_f32_e32 v204, v204
	v_rcp_f32_e32 v205, v205
	v_rcp_f32_e32 v206, v206
	v_rcp_f32_e32 v207, v207
	v_rcp_f32_e32 v208, v208
	v_rcp_f32_e32 v209, v209
	v_mul_f32_e32 v44, v44, v202
	v_mul_f32_e32 v45, v45, v203
	v_mul_f32_e32 v46, v46, v204
	v_mul_f32_e32 v47, v47, v205
	v_mul_f32_e32 v40, v40, v206
	v_mul_f32_e32 v41, v41, v207
	v_mul_f32_e32 v42, v42, v208
	v_mul_f32_e32 v43, v43, v209
	v_cvt_pk_bf16_f32 v44, v44, v45
	v_cvt_pk_bf16_f32 v45, v46, v47
	v_cvt_pk_bf16_f32 v46, v40, v41
	v_cvt_pk_bf16_f32 v47, v42, v43
	global_store_dwordx4 v[128:129], v[44:47], off
	v_mul_f32_e32 v108, v108, v168
	v_mul_f32_e32 v109, v109, v168
	v_mul_f32_e32 v110, v110, v168
	v_mul_f32_e32 v111, v111, v168
	v_mul_f32_e32 v104, v104, v168
	v_mul_f32_e32 v105, v105, v168
	v_mul_f32_e32 v106, v106, v168
	v_mul_f32_e32 v107, v107, v168
	v_mul_f32_e32 v202, 0x3d372713, v108
	v_mul_f32_e32 v203, 0x3d372713, v109
	v_mul_f32_e32 v204, 0x3d372713, v110
	v_mul_f32_e32 v205, 0x3d372713, v111
	v_mul_f32_e32 v206, 0x3d372713, v104
	v_mul_f32_e32 v207, 0x3d372713, v105
	v_mul_f32_e32 v208, 0x3d372713, v106
	v_mul_f32_e32 v209, 0x3d372713, v107
	v_mul_f32_e32 v202, v108, v202
	v_mul_f32_e32 v203, v109, v203
	v_mul_f32_e32 v204, v110, v204
	v_mul_f32_e32 v205, v111, v205
	v_mul_f32_e32 v206, v104, v206
	v_mul_f32_e32 v207, v105, v207
	v_mul_f32_e32 v208, v106, v208
	v_mul_f32_e32 v209, v107, v209
	v_fma_f32 v202, v108, v202, v108
	v_fma_f32 v203, v109, v203, v109
	v_fma_f32 v204, v110, v204, v110
	v_fma_f32 v205, v111, v205, v111
	v_fma_f32 v206, v104, v206, v104
	v_fma_f32 v207, v105, v207, v105
	v_fma_f32 v208, v106, v208, v106
	v_fma_f32 v209, v107, v209, v107
	v_mul_f32_e32 v202, 0x3f4c422a, v202
	v_mul_f32_e32 v203, 0x3f4c422a, v203
	v_mul_f32_e32 v204, 0x3f4c422a, v204
	v_mul_f32_e32 v205, 0x3f4c422a, v205
	v_mul_f32_e32 v206, 0x3f4c422a, v206
	v_mul_f32_e32 v207, 0x3f4c422a, v207
	v_mul_f32_e32 v208, 0x3f4c422a, v208
	v_mul_f32_e32 v209, 0x3f4c422a, v209
	v_mul_f32_e32 v202, 0xc038aa3b, v202
	v_mul_f32_e32 v203, 0xc038aa3b, v203
	v_mul_f32_e32 v204, 0xc038aa3b, v204
	v_mul_f32_e32 v205, 0xc038aa3b, v205
	v_mul_f32_e32 v206, 0xc038aa3b, v206
	v_mul_f32_e32 v207, 0xc038aa3b, v207
	v_mul_f32_e32 v208, 0xc038aa3b, v208
	v_mul_f32_e32 v209, 0xc038aa3b, v209
	v_exp_f32_e32 v202, v202
	v_exp_f32_e32 v203, v203
	v_exp_f32_e32 v204, v204
	v_exp_f32_e32 v205, v205
	v_exp_f32_e32 v206, v206
	v_exp_f32_e32 v207, v207
	v_exp_f32_e32 v208, v208
	v_exp_f32_e32 v209, v209
	v_add_f32_e32 v202, 1.0, v202
	v_add_f32_e32 v203, 1.0, v203
	v_add_f32_e32 v204, 1.0, v204
	v_add_f32_e32 v205, 1.0, v205
	v_add_f32_e32 v206, 1.0, v206
	v_add_f32_e32 v207, 1.0, v207
	v_add_f32_e32 v208, 1.0, v208
	v_add_f32_e32 v209, 1.0, v209
	v_rcp_f32_e32 v202, v202
	v_rcp_f32_e32 v203, v203
	v_rcp_f32_e32 v204, v204
	v_rcp_f32_e32 v205, v205
	v_rcp_f32_e32 v206, v206
	v_rcp_f32_e32 v207, v207
	v_rcp_f32_e32 v208, v208
	v_rcp_f32_e32 v209, v209
	v_mul_f32_e32 v108, v108, v202
	v_mul_f32_e32 v109, v109, v203
	v_mul_f32_e32 v110, v110, v204
	v_mul_f32_e32 v111, v111, v205
	v_mul_f32_e32 v104, v104, v206
	v_mul_f32_e32 v105, v105, v207
	v_mul_f32_e32 v106, v106, v208
	v_mul_f32_e32 v107, v107, v209
	v_cvt_pk_bf16_f32 v108, v108, v109
	v_cvt_pk_bf16_f32 v109, v110, v111
	v_cvt_pk_bf16_f32 v110, v104, v105
	v_cvt_pk_bf16_f32 v111, v106, v107
	global_store_dwordx4 v[128:129], v[108:111], off offset:256
	v_lshl_add_u64 v[128:129], v[128:129], 0, s[100:101]
	v_mul_f32_e32 v36, v36, v166
	v_mul_f32_e32 v37, v37, v166
	v_mul_f32_e32 v38, v38, v166
	v_mul_f32_e32 v39, v39, v166
	v_mul_f32_e32 v32, v32, v166
	v_mul_f32_e32 v33, v33, v166
	v_mul_f32_e32 v34, v34, v166
	v_mul_f32_e32 v35, v35, v166
	v_mul_f32_e32 v202, 0x3d372713, v36
	v_mul_f32_e32 v203, 0x3d372713, v37
	v_mul_f32_e32 v204, 0x3d372713, v38
	v_mul_f32_e32 v205, 0x3d372713, v39
	v_mul_f32_e32 v206, 0x3d372713, v32
	v_mul_f32_e32 v207, 0x3d372713, v33
	v_mul_f32_e32 v208, 0x3d372713, v34
	v_mul_f32_e32 v209, 0x3d372713, v35
	v_mul_f32_e32 v202, v36, v202
	v_mul_f32_e32 v203, v37, v203
	v_mul_f32_e32 v204, v38, v204
	v_mul_f32_e32 v205, v39, v205
	v_mul_f32_e32 v206, v32, v206
	v_mul_f32_e32 v207, v33, v207
	v_mul_f32_e32 v208, v34, v208
	v_mul_f32_e32 v209, v35, v209
	v_fma_f32 v202, v36, v202, v36
	v_fma_f32 v203, v37, v203, v37
	v_fma_f32 v204, v38, v204, v38
	v_fma_f32 v205, v39, v205, v39
	v_fma_f32 v206, v32, v206, v32
	v_fma_f32 v207, v33, v207, v33
	v_fma_f32 v208, v34, v208, v34
	v_fma_f32 v209, v35, v209, v35
	v_mul_f32_e32 v202, 0x3f4c422a, v202
	v_mul_f32_e32 v203, 0x3f4c422a, v203
	v_mul_f32_e32 v204, 0x3f4c422a, v204
	v_mul_f32_e32 v205, 0x3f4c422a, v205
	v_mul_f32_e32 v206, 0x3f4c422a, v206
	v_mul_f32_e32 v207, 0x3f4c422a, v207
	v_mul_f32_e32 v208, 0x3f4c422a, v208
	v_mul_f32_e32 v209, 0x3f4c422a, v209
	v_mul_f32_e32 v202, 0xc038aa3b, v202
	v_mul_f32_e32 v203, 0xc038aa3b, v203
	v_mul_f32_e32 v204, 0xc038aa3b, v204
	v_mul_f32_e32 v205, 0xc038aa3b, v205
	v_mul_f32_e32 v206, 0xc038aa3b, v206
	v_mul_f32_e32 v207, 0xc038aa3b, v207
	v_mul_f32_e32 v208, 0xc038aa3b, v208
	v_mul_f32_e32 v209, 0xc038aa3b, v209
	v_exp_f32_e32 v202, v202
	v_exp_f32_e32 v203, v203
	v_exp_f32_e32 v204, v204
	v_exp_f32_e32 v205, v205
	v_exp_f32_e32 v206, v206
	v_exp_f32_e32 v207, v207
	v_exp_f32_e32 v208, v208
	v_exp_f32_e32 v209, v209
	v_add_f32_e32 v202, 1.0, v202
	v_add_f32_e32 v203, 1.0, v203
	v_add_f32_e32 v204, 1.0, v204
	v_add_f32_e32 v205, 1.0, v205
	v_add_f32_e32 v206, 1.0, v206
	v_add_f32_e32 v207, 1.0, v207
	v_add_f32_e32 v208, 1.0, v208
	v_add_f32_e32 v209, 1.0, v209
	v_rcp_f32_e32 v202, v202
	v_rcp_f32_e32 v203, v203
	v_rcp_f32_e32 v204, v204
	v_rcp_f32_e32 v205, v205
	v_rcp_f32_e32 v206, v206
	v_rcp_f32_e32 v207, v207
	v_rcp_f32_e32 v208, v208
	v_rcp_f32_e32 v209, v209
	v_mul_f32_e32 v36, v36, v202
	v_mul_f32_e32 v37, v37, v203
	v_mul_f32_e32 v38, v38, v204
	v_mul_f32_e32 v39, v39, v205
	v_mul_f32_e32 v32, v32, v206
	v_mul_f32_e32 v33, v33, v207
	v_mul_f32_e32 v34, v34, v208
	v_mul_f32_e32 v35, v35, v209
	v_cvt_pk_bf16_f32 v36, v36, v37
	v_cvt_pk_bf16_f32 v37, v38, v39
	v_cvt_pk_bf16_f32 v38, v32, v33
	v_cvt_pk_bf16_f32 v39, v34, v35
	global_store_dwordx4 v[128:129], v[36:39], off
	v_mul_f32_e32 v100, v100, v166
	v_mul_f32_e32 v101, v101, v166
	v_mul_f32_e32 v102, v102, v166
	v_mul_f32_e32 v103, v103, v166
	v_mul_f32_e32 v96, v96, v166
	v_mul_f32_e32 v97, v97, v166
	v_mul_f32_e32 v98, v98, v166
	v_mul_f32_e32 v99, v99, v166
	v_mul_f32_e32 v202, 0x3d372713, v100
	v_mul_f32_e32 v203, 0x3d372713, v101
	v_mul_f32_e32 v204, 0x3d372713, v102
	v_mul_f32_e32 v205, 0x3d372713, v103
	v_mul_f32_e32 v206, 0x3d372713, v96
	v_mul_f32_e32 v207, 0x3d372713, v97
	v_mul_f32_e32 v208, 0x3d372713, v98
	v_mul_f32_e32 v209, 0x3d372713, v99
	v_mul_f32_e32 v202, v100, v202
	v_mul_f32_e32 v203, v101, v203
	v_mul_f32_e32 v204, v102, v204
	v_mul_f32_e32 v205, v103, v205
	v_mul_f32_e32 v206, v96, v206
	v_mul_f32_e32 v207, v97, v207
	v_mul_f32_e32 v208, v98, v208
	v_mul_f32_e32 v209, v99, v209
	v_fma_f32 v202, v100, v202, v100
	v_fma_f32 v203, v101, v203, v101
	v_fma_f32 v204, v102, v204, v102
	v_fma_f32 v205, v103, v205, v103
	v_fma_f32 v206, v96, v206, v96
	v_fma_f32 v207, v97, v207, v97
	v_fma_f32 v208, v98, v208, v98
	v_fma_f32 v209, v99, v209, v99
	v_mul_f32_e32 v202, 0x3f4c422a, v202
	v_mul_f32_e32 v203, 0x3f4c422a, v203
	v_mul_f32_e32 v204, 0x3f4c422a, v204
	v_mul_f32_e32 v205, 0x3f4c422a, v205
	v_mul_f32_e32 v206, 0x3f4c422a, v206
	v_mul_f32_e32 v207, 0x3f4c422a, v207
	v_mul_f32_e32 v208, 0x3f4c422a, v208
	v_mul_f32_e32 v209, 0x3f4c422a, v209
	v_mul_f32_e32 v202, 0xc038aa3b, v202
	v_mul_f32_e32 v203, 0xc038aa3b, v203
	v_mul_f32_e32 v204, 0xc038aa3b, v204
	v_mul_f32_e32 v205, 0xc038aa3b, v205
	v_mul_f32_e32 v206, 0xc038aa3b, v206
	v_mul_f32_e32 v207, 0xc038aa3b, v207
	v_mul_f32_e32 v208, 0xc038aa3b, v208
	v_mul_f32_e32 v209, 0xc038aa3b, v209
	v_exp_f32_e32 v202, v202
	v_exp_f32_e32 v203, v203
	v_exp_f32_e32 v204, v204
	v_exp_f32_e32 v205, v205
	v_exp_f32_e32 v206, v206
	v_exp_f32_e32 v207, v207
	v_exp_f32_e32 v208, v208
	v_exp_f32_e32 v209, v209
	v_add_f32_e32 v202, 1.0, v202
	v_add_f32_e32 v203, 1.0, v203
	v_add_f32_e32 v204, 1.0, v204
	v_add_f32_e32 v205, 1.0, v205
	v_add_f32_e32 v206, 1.0, v206
	v_add_f32_e32 v207, 1.0, v207
	v_add_f32_e32 v208, 1.0, v208
	v_add_f32_e32 v209, 1.0, v209
	v_rcp_f32_e32 v202, v202
	v_rcp_f32_e32 v203, v203
	v_rcp_f32_e32 v204, v204
	v_rcp_f32_e32 v205, v205
	v_rcp_f32_e32 v206, v206
	v_rcp_f32_e32 v207, v207
	v_rcp_f32_e32 v208, v208
	v_rcp_f32_e32 v209, v209
	v_mul_f32_e32 v100, v100, v202
	v_mul_f32_e32 v101, v101, v203
	v_mul_f32_e32 v102, v102, v204
	v_mul_f32_e32 v103, v103, v205
	v_mul_f32_e32 v96, v96, v206
	v_mul_f32_e32 v97, v97, v207
	v_mul_f32_e32 v98, v98, v208
	v_mul_f32_e32 v99, v99, v209
	v_cvt_pk_bf16_f32 v100, v100, v101
	v_cvt_pk_bf16_f32 v101, v102, v103
	v_cvt_pk_bf16_f32 v102, v96, v97
	v_cvt_pk_bf16_f32 v103, v98, v99
	global_store_dwordx4 v[128:129], v[100:103], off offset:256
	s_mov_b64 s[100:101], 0x96000
	v_lshl_add_u64 v[128:129], v[128:129], 0, s[100:101]
	s_mov_b64 s[100:101], 0x1e000
	v_mul_f32_e32 v28, v28, v162
	v_mul_f32_e32 v29, v29, v162
	v_mul_f32_e32 v30, v30, v162
	v_mul_f32_e32 v31, v31, v162
	v_mul_f32_e32 v24, v24, v162
	v_mul_f32_e32 v25, v25, v162
	v_mul_f32_e32 v26, v26, v162
	v_mul_f32_e32 v27, v27, v162
	v_mul_f32_e32 v202, 0x3d372713, v28
	v_mul_f32_e32 v203, 0x3d372713, v29
	v_mul_f32_e32 v204, 0x3d372713, v30
	v_mul_f32_e32 v205, 0x3d372713, v31
	v_mul_f32_e32 v206, 0x3d372713, v24
	v_mul_f32_e32 v207, 0x3d372713, v25
	v_mul_f32_e32 v208, 0x3d372713, v26
	v_mul_f32_e32 v209, 0x3d372713, v27
	v_mul_f32_e32 v202, v28, v202
	v_mul_f32_e32 v203, v29, v203
	v_mul_f32_e32 v204, v30, v204
	v_mul_f32_e32 v205, v31, v205
	v_mul_f32_e32 v206, v24, v206
	v_mul_f32_e32 v207, v25, v207
	v_mul_f32_e32 v208, v26, v208
	v_mul_f32_e32 v209, v27, v209
	v_fma_f32 v202, v28, v202, v28
	v_fma_f32 v203, v29, v203, v29
	v_fma_f32 v204, v30, v204, v30
	v_fma_f32 v205, v31, v205, v31
	v_fma_f32 v206, v24, v206, v24
	v_fma_f32 v207, v25, v207, v25
	v_fma_f32 v208, v26, v208, v26
	v_fma_f32 v209, v27, v209, v27
	v_mul_f32_e32 v202, 0x3f4c422a, v202
	v_mul_f32_e32 v203, 0x3f4c422a, v203
	v_mul_f32_e32 v204, 0x3f4c422a, v204
	v_mul_f32_e32 v205, 0x3f4c422a, v205
	v_mul_f32_e32 v206, 0x3f4c422a, v206
	v_mul_f32_e32 v207, 0x3f4c422a, v207
	v_mul_f32_e32 v208, 0x3f4c422a, v208
	v_mul_f32_e32 v209, 0x3f4c422a, v209
	v_mul_f32_e32 v202, 0xc038aa3b, v202
	v_mul_f32_e32 v203, 0xc038aa3b, v203
	v_mul_f32_e32 v204, 0xc038aa3b, v204
	v_mul_f32_e32 v205, 0xc038aa3b, v205
	v_mul_f32_e32 v206, 0xc038aa3b, v206
	v_mul_f32_e32 v207, 0xc038aa3b, v207
	v_mul_f32_e32 v208, 0xc038aa3b, v208
	v_mul_f32_e32 v209, 0xc038aa3b, v209
	v_exp_f32_e32 v202, v202
	v_exp_f32_e32 v203, v203
	v_exp_f32_e32 v204, v204
	v_exp_f32_e32 v205, v205
	v_exp_f32_e32 v206, v206
	v_exp_f32_e32 v207, v207
	v_exp_f32_e32 v208, v208
	v_exp_f32_e32 v209, v209
	v_add_f32_e32 v202, 1.0, v202
	v_add_f32_e32 v203, 1.0, v203
	v_add_f32_e32 v204, 1.0, v204
	v_add_f32_e32 v205, 1.0, v205
	v_add_f32_e32 v206, 1.0, v206
	v_add_f32_e32 v207, 1.0, v207
	v_add_f32_e32 v208, 1.0, v208
	v_add_f32_e32 v209, 1.0, v209
	v_rcp_f32_e32 v202, v202
	v_rcp_f32_e32 v203, v203
	v_rcp_f32_e32 v204, v204
	v_rcp_f32_e32 v205, v205
	v_rcp_f32_e32 v206, v206
	v_rcp_f32_e32 v207, v207
	v_rcp_f32_e32 v208, v208
	v_rcp_f32_e32 v209, v209
	v_mul_f32_e32 v28, v28, v202
	v_mul_f32_e32 v29, v29, v203
	v_mul_f32_e32 v30, v30, v204
	v_mul_f32_e32 v31, v31, v205
	v_mul_f32_e32 v24, v24, v206
	v_mul_f32_e32 v25, v25, v207
	v_mul_f32_e32 v26, v26, v208
	v_mul_f32_e32 v27, v27, v209
	v_cvt_pk_bf16_f32 v28, v28, v29
	v_cvt_pk_bf16_f32 v29, v30, v31
	v_cvt_pk_bf16_f32 v30, v24, v25
	v_cvt_pk_bf16_f32 v31, v26, v27
	global_store_dwordx4 v[128:129], v[28:31], off
	v_mul_f32_e32 v92, v92, v162
	v_mul_f32_e32 v93, v93, v162
	v_mul_f32_e32 v94, v94, v162
	v_mul_f32_e32 v95, v95, v162
	v_mul_f32_e32 v88, v88, v162
	v_mul_f32_e32 v89, v89, v162
	v_mul_f32_e32 v90, v90, v162
	v_mul_f32_e32 v91, v91, v162
	v_mul_f32_e32 v202, 0x3d372713, v92
	v_mul_f32_e32 v203, 0x3d372713, v93
	v_mul_f32_e32 v204, 0x3d372713, v94
	v_mul_f32_e32 v205, 0x3d372713, v95
	v_mul_f32_e32 v206, 0x3d372713, v88
	v_mul_f32_e32 v207, 0x3d372713, v89
	v_mul_f32_e32 v208, 0x3d372713, v90
	v_mul_f32_e32 v209, 0x3d372713, v91
	v_mul_f32_e32 v202, v92, v202
	v_mul_f32_e32 v203, v93, v203
	v_mul_f32_e32 v204, v94, v204
	v_mul_f32_e32 v205, v95, v205
	v_mul_f32_e32 v206, v88, v206
	v_mul_f32_e32 v207, v89, v207
	v_mul_f32_e32 v208, v90, v208
	v_mul_f32_e32 v209, v91, v209
	v_fma_f32 v202, v92, v202, v92
	v_fma_f32 v203, v93, v203, v93
	v_fma_f32 v204, v94, v204, v94
	v_fma_f32 v205, v95, v205, v95
	v_fma_f32 v206, v88, v206, v88
	v_fma_f32 v207, v89, v207, v89
	v_fma_f32 v208, v90, v208, v90
	v_fma_f32 v209, v91, v209, v91
	v_mul_f32_e32 v202, 0x3f4c422a, v202
	v_mul_f32_e32 v203, 0x3f4c422a, v203
	v_mul_f32_e32 v204, 0x3f4c422a, v204
	v_mul_f32_e32 v205, 0x3f4c422a, v205
	v_mul_f32_e32 v206, 0x3f4c422a, v206
	v_mul_f32_e32 v207, 0x3f4c422a, v207
	v_mul_f32_e32 v208, 0x3f4c422a, v208
	v_mul_f32_e32 v209, 0x3f4c422a, v209
	v_mul_f32_e32 v202, 0xc038aa3b, v202
	v_mul_f32_e32 v203, 0xc038aa3b, v203
	v_mul_f32_e32 v204, 0xc038aa3b, v204
	v_mul_f32_e32 v205, 0xc038aa3b, v205
	v_mul_f32_e32 v206, 0xc038aa3b, v206
	v_mul_f32_e32 v207, 0xc038aa3b, v207
	v_mul_f32_e32 v208, 0xc038aa3b, v208
	v_mul_f32_e32 v209, 0xc038aa3b, v209
	v_exp_f32_e32 v202, v202
	v_exp_f32_e32 v203, v203
	v_exp_f32_e32 v204, v204
	v_exp_f32_e32 v205, v205
	v_exp_f32_e32 v206, v206
	v_exp_f32_e32 v207, v207
	v_exp_f32_e32 v208, v208
	v_exp_f32_e32 v209, v209
	v_add_f32_e32 v202, 1.0, v202
	v_add_f32_e32 v203, 1.0, v203
	v_add_f32_e32 v204, 1.0, v204
	v_add_f32_e32 v205, 1.0, v205
	v_add_f32_e32 v206, 1.0, v206
	v_add_f32_e32 v207, 1.0, v207
	v_add_f32_e32 v208, 1.0, v208
	v_add_f32_e32 v209, 1.0, v209
	v_rcp_f32_e32 v202, v202
	v_rcp_f32_e32 v203, v203
	v_rcp_f32_e32 v204, v204
	v_rcp_f32_e32 v205, v205
	v_rcp_f32_e32 v206, v206
	v_rcp_f32_e32 v207, v207
	v_rcp_f32_e32 v208, v208
	v_rcp_f32_e32 v209, v209
	v_mul_f32_e32 v92, v92, v202
	v_mul_f32_e32 v93, v93, v203
	v_mul_f32_e32 v94, v94, v204
	v_mul_f32_e32 v95, v95, v205
	v_mul_f32_e32 v88, v88, v206
	v_mul_f32_e32 v89, v89, v207
	v_mul_f32_e32 v90, v90, v208
	v_mul_f32_e32 v91, v91, v209
	v_cvt_pk_bf16_f32 v92, v92, v93
	v_cvt_pk_bf16_f32 v93, v94, v95
	v_cvt_pk_bf16_f32 v94, v88, v89
	v_cvt_pk_bf16_f32 v95, v90, v91
	global_store_dwordx4 v[128:129], v[92:95], off offset:256
	v_lshl_add_u64 v[128:129], v[128:129], 0, s[100:101]
	v_mul_f32_e32 v20, v20, v160
	v_mul_f32_e32 v21, v21, v160
	v_mul_f32_e32 v22, v22, v160
	v_mul_f32_e32 v23, v23, v160
	v_mul_f32_e32 v16, v16, v160
	v_mul_f32_e32 v17, v17, v160
	v_mul_f32_e32 v18, v18, v160
	v_mul_f32_e32 v19, v19, v160
	v_mul_f32_e32 v202, 0x3d372713, v20
	v_mul_f32_e32 v203, 0x3d372713, v21
	v_mul_f32_e32 v204, 0x3d372713, v22
	v_mul_f32_e32 v205, 0x3d372713, v23
	v_mul_f32_e32 v206, 0x3d372713, v16
	v_mul_f32_e32 v207, 0x3d372713, v17
	v_mul_f32_e32 v208, 0x3d372713, v18
	v_mul_f32_e32 v209, 0x3d372713, v19
	v_mul_f32_e32 v202, v20, v202
	v_mul_f32_e32 v203, v21, v203
	v_mul_f32_e32 v204, v22, v204
	v_mul_f32_e32 v205, v23, v205
	v_mul_f32_e32 v206, v16, v206
	v_mul_f32_e32 v207, v17, v207
	v_mul_f32_e32 v208, v18, v208
	v_mul_f32_e32 v209, v19, v209
	v_fma_f32 v202, v20, v202, v20
	v_fma_f32 v203, v21, v203, v21
	v_fma_f32 v204, v22, v204, v22
	v_fma_f32 v205, v23, v205, v23
	v_fma_f32 v206, v16, v206, v16
	v_fma_f32 v207, v17, v207, v17
	v_fma_f32 v208, v18, v208, v18
	v_fma_f32 v209, v19, v209, v19
	v_mul_f32_e32 v202, 0x3f4c422a, v202
	v_mul_f32_e32 v203, 0x3f4c422a, v203
	v_mul_f32_e32 v204, 0x3f4c422a, v204
	v_mul_f32_e32 v205, 0x3f4c422a, v205
	v_mul_f32_e32 v206, 0x3f4c422a, v206
	v_mul_f32_e32 v207, 0x3f4c422a, v207
	v_mul_f32_e32 v208, 0x3f4c422a, v208
	v_mul_f32_e32 v209, 0x3f4c422a, v209
	v_mul_f32_e32 v202, 0xc038aa3b, v202
	v_mul_f32_e32 v203, 0xc038aa3b, v203
	v_mul_f32_e32 v204, 0xc038aa3b, v204
	v_mul_f32_e32 v205, 0xc038aa3b, v205
	v_mul_f32_e32 v206, 0xc038aa3b, v206
	v_mul_f32_e32 v207, 0xc038aa3b, v207
	v_mul_f32_e32 v208, 0xc038aa3b, v208
	v_mul_f32_e32 v209, 0xc038aa3b, v209
	v_exp_f32_e32 v202, v202
	v_exp_f32_e32 v203, v203
	v_exp_f32_e32 v204, v204
	v_exp_f32_e32 v205, v205
	v_exp_f32_e32 v206, v206
	v_exp_f32_e32 v207, v207
	v_exp_f32_e32 v208, v208
	v_exp_f32_e32 v209, v209
	v_add_f32_e32 v202, 1.0, v202
	v_add_f32_e32 v203, 1.0, v203
	v_add_f32_e32 v204, 1.0, v204
	v_add_f32_e32 v205, 1.0, v205
	v_add_f32_e32 v206, 1.0, v206
	v_add_f32_e32 v207, 1.0, v207
	v_add_f32_e32 v208, 1.0, v208
	v_add_f32_e32 v209, 1.0, v209
	v_rcp_f32_e32 v202, v202
	v_rcp_f32_e32 v203, v203
	v_rcp_f32_e32 v204, v204
	v_rcp_f32_e32 v205, v205
	v_rcp_f32_e32 v206, v206
	v_rcp_f32_e32 v207, v207
	v_rcp_f32_e32 v208, v208
	v_rcp_f32_e32 v209, v209
	v_mul_f32_e32 v20, v20, v202
	v_mul_f32_e32 v21, v21, v203
	v_mul_f32_e32 v22, v22, v204
	v_mul_f32_e32 v23, v23, v205
	v_mul_f32_e32 v16, v16, v206
	v_mul_f32_e32 v17, v17, v207
	v_mul_f32_e32 v18, v18, v208
	v_mul_f32_e32 v19, v19, v209
	v_cvt_pk_bf16_f32 v20, v20, v21
	v_cvt_pk_bf16_f32 v21, v22, v23
	v_cvt_pk_bf16_f32 v22, v16, v17
	v_cvt_pk_bf16_f32 v23, v18, v19
	global_store_dwordx4 v[128:129], v[20:23], off
	v_mul_f32_e32 v84, v84, v160
	v_mul_f32_e32 v85, v85, v160
	v_mul_f32_e32 v86, v86, v160
	v_mul_f32_e32 v87, v87, v160
	v_mul_f32_e32 v80, v80, v160
	v_mul_f32_e32 v81, v81, v160
	v_mul_f32_e32 v82, v82, v160
	v_mul_f32_e32 v83, v83, v160
	v_mul_f32_e32 v202, 0x3d372713, v84
	v_mul_f32_e32 v203, 0x3d372713, v85
	v_mul_f32_e32 v204, 0x3d372713, v86
	v_mul_f32_e32 v205, 0x3d372713, v87
	v_mul_f32_e32 v206, 0x3d372713, v80
	v_mul_f32_e32 v207, 0x3d372713, v81
	v_mul_f32_e32 v208, 0x3d372713, v82
	v_mul_f32_e32 v209, 0x3d372713, v83
	v_mul_f32_e32 v202, v84, v202
	v_mul_f32_e32 v203, v85, v203
	v_mul_f32_e32 v204, v86, v204
	v_mul_f32_e32 v205, v87, v205
	v_mul_f32_e32 v206, v80, v206
	v_mul_f32_e32 v207, v81, v207
	v_mul_f32_e32 v208, v82, v208
	v_mul_f32_e32 v209, v83, v209
	v_fma_f32 v202, v84, v202, v84
	v_fma_f32 v203, v85, v203, v85
	v_fma_f32 v204, v86, v204, v86
	v_fma_f32 v205, v87, v205, v87
	v_fma_f32 v206, v80, v206, v80
	v_fma_f32 v207, v81, v207, v81
	v_fma_f32 v208, v82, v208, v82
	v_fma_f32 v209, v83, v209, v83
	v_mul_f32_e32 v202, 0x3f4c422a, v202
	v_mul_f32_e32 v203, 0x3f4c422a, v203
	v_mul_f32_e32 v204, 0x3f4c422a, v204
	v_mul_f32_e32 v205, 0x3f4c422a, v205
	v_mul_f32_e32 v206, 0x3f4c422a, v206
	v_mul_f32_e32 v207, 0x3f4c422a, v207
	v_mul_f32_e32 v208, 0x3f4c422a, v208
	v_mul_f32_e32 v209, 0x3f4c422a, v209
	v_mul_f32_e32 v202, 0xc038aa3b, v202
	v_mul_f32_e32 v203, 0xc038aa3b, v203
	v_mul_f32_e32 v204, 0xc038aa3b, v204
	v_mul_f32_e32 v205, 0xc038aa3b, v205
	v_mul_f32_e32 v206, 0xc038aa3b, v206
	v_mul_f32_e32 v207, 0xc038aa3b, v207
	v_mul_f32_e32 v208, 0xc038aa3b, v208
	v_mul_f32_e32 v209, 0xc038aa3b, v209
	v_exp_f32_e32 v202, v202
	v_exp_f32_e32 v203, v203
	v_exp_f32_e32 v204, v204
	v_exp_f32_e32 v205, v205
	v_exp_f32_e32 v206, v206
	v_exp_f32_e32 v207, v207
	v_exp_f32_e32 v208, v208
	v_exp_f32_e32 v209, v209
	v_add_f32_e32 v202, 1.0, v202
	v_add_f32_e32 v203, 1.0, v203
	v_add_f32_e32 v204, 1.0, v204
	v_add_f32_e32 v205, 1.0, v205
	v_add_f32_e32 v206, 1.0, v206
	v_add_f32_e32 v207, 1.0, v207
	v_add_f32_e32 v208, 1.0, v208
	v_add_f32_e32 v209, 1.0, v209
	v_rcp_f32_e32 v202, v202
	v_rcp_f32_e32 v203, v203
	v_rcp_f32_e32 v204, v204
	v_rcp_f32_e32 v205, v205
	v_rcp_f32_e32 v206, v206
	v_rcp_f32_e32 v207, v207
	v_rcp_f32_e32 v208, v208
	v_rcp_f32_e32 v209, v209
	v_mul_f32_e32 v84, v84, v202
	v_mul_f32_e32 v85, v85, v203
	v_mul_f32_e32 v86, v86, v204
	v_mul_f32_e32 v87, v87, v205
	v_mul_f32_e32 v80, v80, v206
	v_mul_f32_e32 v81, v81, v207
	v_mul_f32_e32 v82, v82, v208
	v_mul_f32_e32 v83, v83, v209
	v_cvt_pk_bf16_f32 v84, v84, v85
	v_cvt_pk_bf16_f32 v85, v86, v87
	v_cvt_pk_bf16_f32 v86, v80, v81
	v_cvt_pk_bf16_f32 v87, v82, v83
	global_store_dwordx4 v[128:129], v[84:87], off offset:256
	v_lshl_add_u64 v[128:129], v[128:129], 0, s[100:101]
	v_mul_f32_e32 v12, v12, v158
	v_mul_f32_e32 v13, v13, v158
	v_mul_f32_e32 v14, v14, v158
	v_mul_f32_e32 v15, v15, v158
	v_mul_f32_e32 v8, v8, v158
	v_mul_f32_e32 v9, v9, v158
	v_mul_f32_e32 v10, v10, v158
	v_mul_f32_e32 v11, v11, v158
	v_mul_f32_e32 v202, 0x3d372713, v12
	v_mul_f32_e32 v203, 0x3d372713, v13
	v_mul_f32_e32 v204, 0x3d372713, v14
	v_mul_f32_e32 v205, 0x3d372713, v15
	v_mul_f32_e32 v206, 0x3d372713, v8
	v_mul_f32_e32 v207, 0x3d372713, v9
	v_mul_f32_e32 v208, 0x3d372713, v10
	v_mul_f32_e32 v209, 0x3d372713, v11
	v_mul_f32_e32 v202, v12, v202
	v_mul_f32_e32 v203, v13, v203
	v_mul_f32_e32 v204, v14, v204
	v_mul_f32_e32 v205, v15, v205
	v_mul_f32_e32 v206, v8, v206
	v_mul_f32_e32 v207, v9, v207
	v_mul_f32_e32 v208, v10, v208
	v_mul_f32_e32 v209, v11, v209
	v_fma_f32 v202, v12, v202, v12
	v_fma_f32 v203, v13, v203, v13
	v_fma_f32 v204, v14, v204, v14
	v_fma_f32 v205, v15, v205, v15
	v_fma_f32 v206, v8, v206, v8
	v_fma_f32 v207, v9, v207, v9
	v_fma_f32 v208, v10, v208, v10
	v_fma_f32 v209, v11, v209, v11
	v_mul_f32_e32 v202, 0x3f4c422a, v202
	v_mul_f32_e32 v203, 0x3f4c422a, v203
	v_mul_f32_e32 v204, 0x3f4c422a, v204
	v_mul_f32_e32 v205, 0x3f4c422a, v205
	v_mul_f32_e32 v206, 0x3f4c422a, v206
	v_mul_f32_e32 v207, 0x3f4c422a, v207
	v_mul_f32_e32 v208, 0x3f4c422a, v208
	v_mul_f32_e32 v209, 0x3f4c422a, v209
	v_mul_f32_e32 v202, 0xc038aa3b, v202
	v_mul_f32_e32 v203, 0xc038aa3b, v203
	v_mul_f32_e32 v204, 0xc038aa3b, v204
	v_mul_f32_e32 v205, 0xc038aa3b, v205
	v_mul_f32_e32 v206, 0xc038aa3b, v206
	v_mul_f32_e32 v207, 0xc038aa3b, v207
	v_mul_f32_e32 v208, 0xc038aa3b, v208
	v_mul_f32_e32 v209, 0xc038aa3b, v209
	v_exp_f32_e32 v202, v202
	v_exp_f32_e32 v203, v203
	v_exp_f32_e32 v204, v204
	v_exp_f32_e32 v205, v205
	v_exp_f32_e32 v206, v206
	v_exp_f32_e32 v207, v207
	v_exp_f32_e32 v208, v208
	v_exp_f32_e32 v209, v209
	v_add_f32_e32 v202, 1.0, v202
	v_add_f32_e32 v203, 1.0, v203
	v_add_f32_e32 v204, 1.0, v204
	v_add_f32_e32 v205, 1.0, v205
	v_add_f32_e32 v206, 1.0, v206
	v_add_f32_e32 v207, 1.0, v207
	v_add_f32_e32 v208, 1.0, v208
	v_add_f32_e32 v209, 1.0, v209
	v_rcp_f32_e32 v202, v202
	v_rcp_f32_e32 v203, v203
	v_rcp_f32_e32 v204, v204
	v_rcp_f32_e32 v205, v205
	v_rcp_f32_e32 v206, v206
	v_rcp_f32_e32 v207, v207
	v_rcp_f32_e32 v208, v208
	v_rcp_f32_e32 v209, v209
	v_mul_f32_e32 v12, v12, v202
	v_mul_f32_e32 v13, v13, v203
	v_mul_f32_e32 v14, v14, v204
	v_mul_f32_e32 v15, v15, v205
	v_mul_f32_e32 v8, v8, v206
	v_mul_f32_e32 v9, v9, v207
	v_mul_f32_e32 v10, v10, v208
	v_mul_f32_e32 v11, v11, v209
	v_cvt_pk_bf16_f32 v12, v12, v13
	v_cvt_pk_bf16_f32 v13, v14, v15
	v_cvt_pk_bf16_f32 v14, v8, v9
	v_cvt_pk_bf16_f32 v15, v10, v11
	global_store_dwordx4 v[128:129], v[12:15], off
	v_mul_f32_e32 v76, v76, v158
	v_mul_f32_e32 v77, v77, v158
	v_mul_f32_e32 v78, v78, v158
	v_mul_f32_e32 v79, v79, v158
	v_mul_f32_e32 v72, v72, v158
	v_mul_f32_e32 v73, v73, v158
	v_mul_f32_e32 v74, v74, v158
	v_mul_f32_e32 v75, v75, v158
	v_mul_f32_e32 v202, 0x3d372713, v76
	v_mul_f32_e32 v203, 0x3d372713, v77
	v_mul_f32_e32 v204, 0x3d372713, v78
	v_mul_f32_e32 v205, 0x3d372713, v79
	v_mul_f32_e32 v206, 0x3d372713, v72
	v_mul_f32_e32 v207, 0x3d372713, v73
	v_mul_f32_e32 v208, 0x3d372713, v74
	v_mul_f32_e32 v209, 0x3d372713, v75
	v_mul_f32_e32 v202, v76, v202
	v_mul_f32_e32 v203, v77, v203
	v_mul_f32_e32 v204, v78, v204
	v_mul_f32_e32 v205, v79, v205
	v_mul_f32_e32 v206, v72, v206
	v_mul_f32_e32 v207, v73, v207
	v_mul_f32_e32 v208, v74, v208
	v_mul_f32_e32 v209, v75, v209
	v_fma_f32 v202, v76, v202, v76
	v_fma_f32 v203, v77, v203, v77
	v_fma_f32 v204, v78, v204, v78
	v_fma_f32 v205, v79, v205, v79
	v_fma_f32 v206, v72, v206, v72
	v_fma_f32 v207, v73, v207, v73
	v_fma_f32 v208, v74, v208, v74
	v_fma_f32 v209, v75, v209, v75
	v_mul_f32_e32 v202, 0x3f4c422a, v202
	v_mul_f32_e32 v203, 0x3f4c422a, v203
	v_mul_f32_e32 v204, 0x3f4c422a, v204
	v_mul_f32_e32 v205, 0x3f4c422a, v205
	v_mul_f32_e32 v206, 0x3f4c422a, v206
	v_mul_f32_e32 v207, 0x3f4c422a, v207
	v_mul_f32_e32 v208, 0x3f4c422a, v208
	v_mul_f32_e32 v209, 0x3f4c422a, v209
	v_mul_f32_e32 v202, 0xc038aa3b, v202
	v_mul_f32_e32 v203, 0xc038aa3b, v203
	v_mul_f32_e32 v204, 0xc038aa3b, v204
	v_mul_f32_e32 v205, 0xc038aa3b, v205
	v_mul_f32_e32 v206, 0xc038aa3b, v206
	v_mul_f32_e32 v207, 0xc038aa3b, v207
	v_mul_f32_e32 v208, 0xc038aa3b, v208
	v_mul_f32_e32 v209, 0xc038aa3b, v209
	v_exp_f32_e32 v202, v202
	v_exp_f32_e32 v203, v203
	v_exp_f32_e32 v204, v204
	v_exp_f32_e32 v205, v205
	v_exp_f32_e32 v206, v206
	v_exp_f32_e32 v207, v207
	v_exp_f32_e32 v208, v208
	v_exp_f32_e32 v209, v209
	v_add_f32_e32 v202, 1.0, v202
	v_add_f32_e32 v203, 1.0, v203
	v_add_f32_e32 v204, 1.0, v204
	v_add_f32_e32 v205, 1.0, v205
	v_add_f32_e32 v206, 1.0, v206
	v_add_f32_e32 v207, 1.0, v207
	v_add_f32_e32 v208, 1.0, v208
	v_add_f32_e32 v209, 1.0, v209
	v_rcp_f32_e32 v202, v202
	v_rcp_f32_e32 v203, v203
	v_rcp_f32_e32 v204, v204
	v_rcp_f32_e32 v205, v205
	v_rcp_f32_e32 v206, v206
	v_rcp_f32_e32 v207, v207
	v_rcp_f32_e32 v208, v208
	v_rcp_f32_e32 v209, v209
	v_mul_f32_e32 v76, v76, v202
	v_mul_f32_e32 v77, v77, v203
	v_mul_f32_e32 v78, v78, v204
	v_mul_f32_e32 v79, v79, v205
	v_mul_f32_e32 v72, v72, v206
	v_mul_f32_e32 v73, v73, v207
	v_mul_f32_e32 v74, v74, v208
	v_mul_f32_e32 v75, v75, v209
	v_cvt_pk_bf16_f32 v76, v76, v77
	v_cvt_pk_bf16_f32 v77, v78, v79
	v_cvt_pk_bf16_f32 v78, v72, v73
	v_cvt_pk_bf16_f32 v79, v74, v75
	global_store_dwordx4 v[128:129], v[76:79], off offset:256
	v_lshl_add_u64 v[128:129], v[128:129], 0, s[100:101]
	v_mul_f32_e32 v4, v4, v156
	v_mul_f32_e32 v5, v5, v156
	v_mul_f32_e32 v6, v6, v156
	v_mul_f32_e32 v7, v7, v156
	v_mul_f32_e32 v0, v0, v156
	v_mul_f32_e32 v1, v1, v156
	v_mul_f32_e32 v2, v2, v156
	v_mul_f32_e32 v3, v3, v156
	v_mul_f32_e32 v202, 0x3d372713, v4
	v_mul_f32_e32 v203, 0x3d372713, v5
	v_mul_f32_e32 v204, 0x3d372713, v6
	v_mul_f32_e32 v205, 0x3d372713, v7
	v_mul_f32_e32 v206, 0x3d372713, v0
	v_mul_f32_e32 v207, 0x3d372713, v1
	v_mul_f32_e32 v208, 0x3d372713, v2
	v_mul_f32_e32 v209, 0x3d372713, v3
	v_mul_f32_e32 v202, v4, v202
	v_mul_f32_e32 v203, v5, v203
	v_mul_f32_e32 v204, v6, v204
	v_mul_f32_e32 v205, v7, v205
	v_mul_f32_e32 v206, v0, v206
	v_mul_f32_e32 v207, v1, v207
	v_mul_f32_e32 v208, v2, v208
	v_mul_f32_e32 v209, v3, v209
	v_fma_f32 v202, v4, v202, v4
	v_fma_f32 v203, v5, v203, v5
	v_fma_f32 v204, v6, v204, v6
	v_fma_f32 v205, v7, v205, v7
	v_fma_f32 v206, v0, v206, v0
	v_fma_f32 v207, v1, v207, v1
	v_fma_f32 v208, v2, v208, v2
	v_fma_f32 v209, v3, v209, v3
	v_mul_f32_e32 v202, 0x3f4c422a, v202
	v_mul_f32_e32 v203, 0x3f4c422a, v203
	v_mul_f32_e32 v204, 0x3f4c422a, v204
	v_mul_f32_e32 v205, 0x3f4c422a, v205
	v_mul_f32_e32 v206, 0x3f4c422a, v206
	v_mul_f32_e32 v207, 0x3f4c422a, v207
	v_mul_f32_e32 v208, 0x3f4c422a, v208
	v_mul_f32_e32 v209, 0x3f4c422a, v209
	v_mul_f32_e32 v202, 0xc038aa3b, v202
	v_mul_f32_e32 v203, 0xc038aa3b, v203
	v_mul_f32_e32 v204, 0xc038aa3b, v204
	v_mul_f32_e32 v205, 0xc038aa3b, v205
	v_mul_f32_e32 v206, 0xc038aa3b, v206
	v_mul_f32_e32 v207, 0xc038aa3b, v207
	v_mul_f32_e32 v208, 0xc038aa3b, v208
	v_mul_f32_e32 v209, 0xc038aa3b, v209
	v_exp_f32_e32 v202, v202
	v_exp_f32_e32 v203, v203
	v_exp_f32_e32 v204, v204
	v_exp_f32_e32 v205, v205
	v_exp_f32_e32 v206, v206
	v_exp_f32_e32 v207, v207
	v_exp_f32_e32 v208, v208
	v_exp_f32_e32 v209, v209
	v_add_f32_e32 v202, 1.0, v202
	v_add_f32_e32 v203, 1.0, v203
	v_add_f32_e32 v204, 1.0, v204
	v_add_f32_e32 v205, 1.0, v205
	v_add_f32_e32 v206, 1.0, v206
	v_add_f32_e32 v207, 1.0, v207
	v_add_f32_e32 v208, 1.0, v208
	v_add_f32_e32 v209, 1.0, v209
	v_rcp_f32_e32 v202, v202
	v_rcp_f32_e32 v203, v203
	v_rcp_f32_e32 v204, v204
	v_rcp_f32_e32 v205, v205
	v_rcp_f32_e32 v206, v206
	v_rcp_f32_e32 v207, v207
	v_rcp_f32_e32 v208, v208
	v_rcp_f32_e32 v209, v209
	v_mul_f32_e32 v4, v4, v202
	v_mul_f32_e32 v5, v5, v203
	v_mul_f32_e32 v6, v6, v204
	v_mul_f32_e32 v7, v7, v205
	v_mul_f32_e32 v0, v0, v206
	v_mul_f32_e32 v1, v1, v207
	v_mul_f32_e32 v2, v2, v208
	v_mul_f32_e32 v3, v3, v209
	v_cvt_pk_bf16_f32 v4, v4, v5
	v_cvt_pk_bf16_f32 v5, v6, v7
	v_cvt_pk_bf16_f32 v6, v0, v1
	v_cvt_pk_bf16_f32 v7, v2, v3
	global_store_dwordx4 v[128:129], v[4:7], off
	v_mul_f32_e32 v68, v68, v156
	v_mul_f32_e32 v69, v69, v156
	v_mul_f32_e32 v70, v70, v156
	v_mul_f32_e32 v71, v71, v156
	v_mul_f32_e32 v64, v64, v156
	v_mul_f32_e32 v65, v65, v156
	v_mul_f32_e32 v66, v66, v156
	v_mul_f32_e32 v67, v67, v156
	v_mul_f32_e32 v202, 0x3d372713, v68
	v_mul_f32_e32 v203, 0x3d372713, v69
	v_mul_f32_e32 v204, 0x3d372713, v70
	v_mul_f32_e32 v205, 0x3d372713, v71
	v_mul_f32_e32 v206, 0x3d372713, v64
	v_mul_f32_e32 v207, 0x3d372713, v65
	v_mul_f32_e32 v208, 0x3d372713, v66
	v_mul_f32_e32 v209, 0x3d372713, v67
	v_mul_f32_e32 v202, v68, v202
	v_mul_f32_e32 v203, v69, v203
	v_mul_f32_e32 v204, v70, v204
	v_mul_f32_e32 v205, v71, v205
	v_mul_f32_e32 v206, v64, v206
	v_mul_f32_e32 v207, v65, v207
	v_mul_f32_e32 v208, v66, v208
	v_mul_f32_e32 v209, v67, v209
	v_fma_f32 v202, v68, v202, v68
	v_fma_f32 v203, v69, v203, v69
	v_fma_f32 v204, v70, v204, v70
	v_fma_f32 v205, v71, v205, v71
	v_fma_f32 v206, v64, v206, v64
	v_fma_f32 v207, v65, v207, v65
	v_fma_f32 v208, v66, v208, v66
	v_fma_f32 v209, v67, v209, v67
	v_mul_f32_e32 v202, 0x3f4c422a, v202
	v_mul_f32_e32 v203, 0x3f4c422a, v203
	v_mul_f32_e32 v204, 0x3f4c422a, v204
	v_mul_f32_e32 v205, 0x3f4c422a, v205
	v_mul_f32_e32 v206, 0x3f4c422a, v206
	v_mul_f32_e32 v207, 0x3f4c422a, v207
	v_mul_f32_e32 v208, 0x3f4c422a, v208
	v_mul_f32_e32 v209, 0x3f4c422a, v209
	v_mul_f32_e32 v202, 0xc038aa3b, v202
	v_mul_f32_e32 v203, 0xc038aa3b, v203
	v_mul_f32_e32 v204, 0xc038aa3b, v204
	v_mul_f32_e32 v205, 0xc038aa3b, v205
	v_mul_f32_e32 v206, 0xc038aa3b, v206
	v_mul_f32_e32 v207, 0xc038aa3b, v207
	v_mul_f32_e32 v208, 0xc038aa3b, v208
	v_mul_f32_e32 v209, 0xc038aa3b, v209
	v_exp_f32_e32 v202, v202
	v_exp_f32_e32 v203, v203
	v_exp_f32_e32 v204, v204
	v_exp_f32_e32 v205, v205
	v_exp_f32_e32 v206, v206
	v_exp_f32_e32 v207, v207
	v_exp_f32_e32 v208, v208
	v_exp_f32_e32 v209, v209
	v_add_f32_e32 v202, 1.0, v202
	v_add_f32_e32 v203, 1.0, v203
	v_add_f32_e32 v204, 1.0, v204
	v_add_f32_e32 v205, 1.0, v205
	v_add_f32_e32 v206, 1.0, v206
	v_add_f32_e32 v207, 1.0, v207
	v_add_f32_e32 v208, 1.0, v208
	v_add_f32_e32 v209, 1.0, v209
	v_rcp_f32_e32 v202, v202
	v_rcp_f32_e32 v203, v203
	v_rcp_f32_e32 v204, v204
	v_rcp_f32_e32 v205, v205
	v_rcp_f32_e32 v206, v206
	v_rcp_f32_e32 v207, v207
	v_rcp_f32_e32 v208, v208
	v_rcp_f32_e32 v209, v209
	v_mul_f32_e32 v68, v68, v202
	v_mul_f32_e32 v69, v69, v203
	v_mul_f32_e32 v70, v70, v204
	v_mul_f32_e32 v71, v71, v205
	v_mul_f32_e32 v64, v64, v206
	v_mul_f32_e32 v65, v65, v207
	v_mul_f32_e32 v66, v66, v208
	v_mul_f32_e32 v67, v67, v209
	v_cvt_pk_bf16_f32 v68, v68, v69
	v_cvt_pk_bf16_f32 v69, v70, v71
	v_cvt_pk_bf16_f32 v70, v64, v65
	v_cvt_pk_bf16_f32 v71, v66, v67
	global_store_dwordx4 v[128:129], v[68:71], off offset:256
	s_branch .LBB0_271
